# scan: producers store 0.25*br, 0.25*kr; consumer adds the two y terms with two fmacs (one VALU op less per step)
# baseline (speedup 1.0000x reference)
.LBB0_1252:
	s_and_b32 s5, s4, 32
	s_mulk_i32 s5, 0x560
	s_add_i32 s5, s5, 0
	s_barrier
	v_lshl_add_u32 v16, v7, 2, s5
	v_lshl_add_u32 v18, v12, 2, s5
	v_mov_b32_e32 v19, s5
	v_add_u32_e32 v17, v16, v11
	ds_read_b128 v[100:103], v17 offset:0
	ds_read_b128 v[104:107], v17 offset:256
	ds_read_b128 v[116:119], v17 offset:1024
	ds_read_b128 v[108:111], v17 offset:512
	ds_read_b128 v[112:115], v17 offset:768
	ds_read_b32 v120, v18 offset:1280
	ds_read_b64 v[122:123], v19 offset:1344
	ds_read_b128 v[156:159], v17 offset:1376
	ds_read_b128 v[160:163], v17 offset:1632
	ds_read_b128 v[172:175], v17 offset:2400
	ds_read_b128 v[164:167], v17 offset:1888
	ds_read_b128 v[168:171], v17 offset:2144
	ds_read_b32 v176, v18 offset:2656
	ds_read_b64 v[178:179], v19 offset:2720
	s_waitcnt lgkmcnt(7)
	ds_read_b128 v[180:183], v17 offset:2752
	ds_read_b128 v[184:187], v17 offset:3008
	ds_read_b128 v[196:199], v17 offset:3776
	ds_read_b128 v[188:191], v17 offset:3264
	ds_read_b128 v[192:195], v17 offset:3520
	v_pk_mul_f32 v[20:21], v[2:3], v[100:101] op_sel_hi:[0,1]
	v_pk_fma_f32 v[20:21], v[102:103], v[2:3], v[20:21] op_sel:[0,1,0]
	v_pk_fma_f32 v[20:21], v[104:105], v[4:5], v[20:21] op_sel_hi:[1,0,1]
	v_pk_fma_f32 v[20:21], v[106:107], v[4:5], v[20:21] op_sel:[0,1,0]
	v_pk_mul_f32 v[22:23], v[116:117], v[120:121] op_sel_hi:[1,0]
	v_pk_mul_f32 v[24:25], v[118:119], v[120:121] op_sel_hi:[1,0]
	v_add_f32_dpp v26, v20, v20 row_ror:8 row_mask:0xf bank_mask:0xf bound_ctrl:1
	v_add_f32_dpp v28, v21, v21 row_ror:8 row_mask:0xf bank_mask:0xf bound_ctrl:1
	v_pk_fma_f32 v[22:23], v[2:3], v[108:109], v[22:23]
	v_add_f32_dpp v26, v26, v26 row_ror:4 row_mask:0xf bank_mask:0xf bound_ctrl:1
	v_pk_fma_f32 v[24:25], v[4:5], v[110:111], v[24:25]
	v_add_f32_dpp v28, v28, v28 row_ror:4 row_mask:0xf bank_mask:0xf bound_ctrl:1
	v_add_f32_dpp v26, v26, v26 row_ror:2 row_mask:0xf bank_mask:0xf bound_ctrl:1
	ds_read_b32 v200, v18 offset:4032
	ds_read_b64 v[202:203], v19 offset:4096
	v_add_f32_dpp v26, v26, v26 row_ror:1 row_mask:0xf bank_mask:0xf bound_ctrl:1
	v_pk_fma_f32 v[2:3], v[112:113], v[26:27], v[22:23] op_sel_hi:[1,0,1]
	v_pk_fma_f32 v[4:5], v[114:115], v[26:27], v[24:25] op_sel_hi:[1,0,1]
	v_fmac_f32_e32 v28, v122, v26
	v_fmac_f32_e32 v28, v120, v123
	ds_write_b32 v9, v28
	s_waitcnt lgkmcnt(8)
	ds_read_b128 v[100:103], v17 offset:4128
	ds_read_b128 v[104:107], v17 offset:4384
	ds_read_b128 v[116:119], v17 offset:5152
	ds_read_b128 v[108:111], v17 offset:4640
	ds_read_b128 v[112:115], v17 offset:4896
	v_pk_mul_f32 v[20:21], v[2:3], v[156:157] op_sel_hi:[0,1]
	v_pk_fma_f32 v[20:21], v[158:159], v[2:3], v[20:21] op_sel:[0,1,0]
	v_pk_fma_f32 v[20:21], v[160:161], v[4:5], v[20:21] op_sel_hi:[1,0,1]
	v_pk_fma_f32 v[20:21], v[162:163], v[4:5], v[20:21] op_sel:[0,1,0]
	v_pk_mul_f32 v[22:23], v[172:173], v[176:177] op_sel_hi:[1,0]
	v_pk_mul_f32 v[24:25], v[174:175], v[176:177] op_sel_hi:[1,0]
	v_add_f32_dpp v26, v20, v20 row_ror:8 row_mask:0xf bank_mask:0xf bound_ctrl:1
	v_add_f32_dpp v28, v21, v21 row_ror:8 row_mask:0xf bank_mask:0xf bound_ctrl:1
	v_pk_fma_f32 v[22:23], v[2:3], v[164:165], v[22:23]
	v_add_f32_dpp v26, v26, v26 row_ror:4 row_mask:0xf bank_mask:0xf bound_ctrl:1
	v_pk_fma_f32 v[24:25], v[4:5], v[166:167], v[24:25]
	v_add_f32_dpp v28, v28, v28 row_ror:4 row_mask:0xf bank_mask:0xf bound_ctrl:1
	v_add_f32_dpp v26, v26, v26 row_ror:2 row_mask:0xf bank_mask:0xf bound_ctrl:1
	ds_read_b32 v120, v18 offset:5408
	ds_read_b64 v[122:123], v19 offset:5472
	v_add_f32_dpp v26, v26, v26 row_ror:1 row_mask:0xf bank_mask:0xf bound_ctrl:1
	v_pk_fma_f32 v[2:3], v[168:169], v[26:27], v[22:23] op_sel_hi:[1,0,1]
	v_pk_fma_f32 v[4:5], v[170:171], v[26:27], v[24:25] op_sel_hi:[1,0,1]
	v_fmac_f32_e32 v28, v178, v26
	v_fmac_f32_e32 v28, v176, v179
	ds_write_b32 v9, v28 offset:64
	s_waitcnt lgkmcnt(9)
	ds_read_b128 v[156:159], v17 offset:5504
	ds_read_b128 v[160:163], v17 offset:5760
	ds_read_b128 v[172:175], v17 offset:6528
	ds_read_b128 v[164:167], v17 offset:6016
	ds_read_b128 v[168:171], v17 offset:6272
	v_pk_mul_f32 v[20:21], v[2:3], v[180:181] op_sel_hi:[0,1]
	v_pk_fma_f32 v[20:21], v[182:183], v[2:3], v[20:21] op_sel:[0,1,0]
	v_pk_fma_f32 v[20:21], v[184:185], v[4:5], v[20:21] op_sel_hi:[1,0,1]
	v_pk_fma_f32 v[20:21], v[186:187], v[4:5], v[20:21] op_sel:[0,1,0]
	v_pk_mul_f32 v[22:23], v[196:197], v[200:201] op_sel_hi:[1,0]
	v_pk_mul_f32 v[24:25], v[198:199], v[200:201] op_sel_hi:[1,0]
	v_add_f32_dpp v26, v20, v20 row_ror:8 row_mask:0xf bank_mask:0xf bound_ctrl:1
	v_add_f32_dpp v28, v21, v21 row_ror:8 row_mask:0xf bank_mask:0xf bound_ctrl:1
	v_pk_fma_f32 v[22:23], v[2:3], v[188:189], v[22:23]
	v_add_f32_dpp v26, v26, v26 row_ror:4 row_mask:0xf bank_mask:0xf bound_ctrl:1
	v_pk_fma_f32 v[24:25], v[4:5], v[190:191], v[24:25]
	v_add_f32_dpp v28, v28, v28 row_ror:4 row_mask:0xf bank_mask:0xf bound_ctrl:1
	v_add_f32_dpp v26, v26, v26 row_ror:2 row_mask:0xf bank_mask:0xf bound_ctrl:1
	ds_read_b32 v176, v18 offset:6784
	ds_read_b64 v[178:179], v19 offset:6848
	v_add_f32_dpp v26, v26, v26 row_ror:1 row_mask:0xf bank_mask:0xf bound_ctrl:1
	v_pk_fma_f32 v[2:3], v[192:193], v[26:27], v[22:23] op_sel_hi:[1,0,1]
	v_pk_fma_f32 v[4:5], v[194:195], v[26:27], v[24:25] op_sel_hi:[1,0,1]
	v_fmac_f32_e32 v28, v202, v26
	v_fmac_f32_e32 v28, v200, v203
	ds_write_b32 v9, v28 offset:128
	s_waitcnt lgkmcnt(9)
	ds_read_b128 v[180:183], v17 offset:6880
	ds_read_b128 v[184:187], v17 offset:7136
	ds_read_b128 v[196:199], v17 offset:7904
	ds_read_b128 v[188:191], v17 offset:7392
	ds_read_b128 v[192:195], v17 offset:7648
	v_pk_mul_f32 v[20:21], v[2:3], v[100:101] op_sel_hi:[0,1]
	v_pk_fma_f32 v[20:21], v[102:103], v[2:3], v[20:21] op_sel:[0,1,0]
	v_pk_fma_f32 v[20:21], v[104:105], v[4:5], v[20:21] op_sel_hi:[1,0,1]
	v_pk_fma_f32 v[20:21], v[106:107], v[4:5], v[20:21] op_sel:[0,1,0]
	v_pk_mul_f32 v[22:23], v[116:117], v[120:121] op_sel_hi:[1,0]
	v_pk_mul_f32 v[24:25], v[118:119], v[120:121] op_sel_hi:[1,0]
	v_add_f32_dpp v26, v20, v20 row_ror:8 row_mask:0xf bank_mask:0xf bound_ctrl:1
	v_add_f32_dpp v28, v21, v21 row_ror:8 row_mask:0xf bank_mask:0xf bound_ctrl:1
	v_pk_fma_f32 v[22:23], v[2:3], v[108:109], v[22:23]
	v_add_f32_dpp v26, v26, v26 row_ror:4 row_mask:0xf bank_mask:0xf bound_ctrl:1
	v_pk_fma_f32 v[24:25], v[4:5], v[110:111], v[24:25]
	v_add_f32_dpp v28, v28, v28 row_ror:4 row_mask:0xf bank_mask:0xf bound_ctrl:1
	v_add_f32_dpp v26, v26, v26 row_ror:2 row_mask:0xf bank_mask:0xf bound_ctrl:1
	ds_read_b32 v200, v18 offset:8160
	ds_read_b64 v[202:203], v19 offset:8224
	v_add_f32_dpp v26, v26, v26 row_ror:1 row_mask:0xf bank_mask:0xf bound_ctrl:1
	v_pk_fma_f32 v[2:3], v[112:113], v[26:27], v[22:23] op_sel_hi:[1,0,1]
	v_pk_fma_f32 v[4:5], v[114:115], v[26:27], v[24:25] op_sel_hi:[1,0,1]
	v_fmac_f32_e32 v28, v122, v26
	v_fmac_f32_e32 v28, v120, v123
	ds_write_b32 v9, v28 offset:192
	s_waitcnt lgkmcnt(9)
	ds_read_b128 v[100:103], v17 offset:8256
	ds_read_b128 v[104:107], v17 offset:8512
	ds_read_b128 v[116:119], v17 offset:9280
	ds_read_b128 v[108:111], v17 offset:8768
	ds_read_b128 v[112:115], v17 offset:9024
	v_pk_mul_f32 v[20:21], v[2:3], v[156:157] op_sel_hi:[0,1]
	v_pk_fma_f32 v[20:21], v[158:159], v[2:3], v[20:21] op_sel:[0,1,0]
	v_pk_fma_f32 v[20:21], v[160:161], v[4:5], v[20:21] op_sel_hi:[1,0,1]
	v_pk_fma_f32 v[20:21], v[162:163], v[4:5], v[20:21] op_sel:[0,1,0]
	v_pk_mul_f32 v[22:23], v[172:173], v[176:177] op_sel_hi:[1,0]
	v_pk_mul_f32 v[24:25], v[174:175], v[176:177] op_sel_hi:[1,0]
	v_add_f32_dpp v26, v20, v20 row_ror:8 row_mask:0xf bank_mask:0xf bound_ctrl:1
	v_add_f32_dpp v28, v21, v21 row_ror:8 row_mask:0xf bank_mask:0xf bound_ctrl:1
	v_pk_fma_f32 v[22:23], v[2:3], v[164:165], v[22:23]
	v_add_f32_dpp v26, v26, v26 row_ror:4 row_mask:0xf bank_mask:0xf bound_ctrl:1
	v_pk_fma_f32 v[24:25], v[4:5], v[166:167], v[24:25]
	v_add_f32_dpp v28, v28, v28 row_ror:4 row_mask:0xf bank_mask:0xf bound_ctrl:1
	v_add_f32_dpp v26, v26, v26 row_ror:2 row_mask:0xf bank_mask:0xf bound_ctrl:1
	ds_read_b32 v120, v18 offset:9536
	ds_read_b64 v[122:123], v19 offset:9600
	v_add_f32_dpp v26, v26, v26 row_ror:1 row_mask:0xf bank_mask:0xf bound_ctrl:1
	v_pk_fma_f32 v[2:3], v[168:169], v[26:27], v[22:23] op_sel_hi:[1,0,1]
	v_pk_fma_f32 v[4:5], v[170:171], v[26:27], v[24:25] op_sel_hi:[1,0,1]
	v_fmac_f32_e32 v28, v178, v26
	v_fmac_f32_e32 v28, v176, v179
	ds_write_b32 v9, v28 offset:256
	s_waitcnt lgkmcnt(9)
	ds_read_b128 v[156:159], v17 offset:9632
	ds_read_b128 v[160:163], v17 offset:9888
	ds_read_b128 v[172:175], v17 offset:10656
	ds_read_b128 v[164:167], v17 offset:10144
	ds_read_b128 v[168:171], v17 offset:10400
	v_pk_mul_f32 v[20:21], v[2:3], v[180:181] op_sel_hi:[0,1]
	v_pk_fma_f32 v[20:21], v[182:183], v[2:3], v[20:21] op_sel:[0,1,0]
	v_pk_fma_f32 v[20:21], v[184:185], v[4:5], v[20:21] op_sel_hi:[1,0,1]
	v_pk_fma_f32 v[20:21], v[186:187], v[4:5], v[20:21] op_sel:[0,1,0]
	v_pk_mul_f32 v[22:23], v[196:197], v[200:201] op_sel_hi:[1,0]
	v_pk_mul_f32 v[24:25], v[198:199], v[200:201] op_sel_hi:[1,0]
	v_add_f32_dpp v26, v20, v20 row_ror:8 row_mask:0xf bank_mask:0xf bound_ctrl:1
	v_add_f32_dpp v28, v21, v21 row_ror:8 row_mask:0xf bank_mask:0xf bound_ctrl:1
	v_pk_fma_f32 v[22:23], v[2:3], v[188:189], v[22:23]
	v_add_f32_dpp v26, v26, v26 row_ror:4 row_mask:0xf bank_mask:0xf bound_ctrl:1
	v_pk_fma_f32 v[24:25], v[4:5], v[190:191], v[24:25]
	v_add_f32_dpp v28, v28, v28 row_ror:4 row_mask:0xf bank_mask:0xf bound_ctrl:1
	v_add_f32_dpp v26, v26, v26 row_ror:2 row_mask:0xf bank_mask:0xf bound_ctrl:1
	ds_read_b32 v176, v18 offset:10912
	ds_read_b64 v[178:179], v19 offset:10976
	v_add_f32_dpp v26, v26, v26 row_ror:1 row_mask:0xf bank_mask:0xf bound_ctrl:1
	v_pk_fma_f32 v[2:3], v[192:193], v[26:27], v[22:23] op_sel_hi:[1,0,1]
	v_pk_fma_f32 v[4:5], v[194:195], v[26:27], v[24:25] op_sel_hi:[1,0,1]
	v_fmac_f32_e32 v28, v202, v26
	v_fmac_f32_e32 v28, v200, v203
	ds_write_b32 v9, v28 offset:320
	s_waitcnt lgkmcnt(9)
	ds_read_b128 v[180:183], v17 offset:11008
	ds_read_b128 v[184:187], v17 offset:11264
	ds_read_b128 v[196:199], v17 offset:12032
	ds_read_b128 v[188:191], v17 offset:11520
	ds_read_b128 v[192:195], v17 offset:11776
	v_pk_mul_f32 v[20:21], v[2:3], v[100:101] op_sel_hi:[0,1]
	v_pk_fma_f32 v[20:21], v[102:103], v[2:3], v[20:21] op_sel:[0,1,0]
	v_pk_fma_f32 v[20:21], v[104:105], v[4:5], v[20:21] op_sel_hi:[1,0,1]
	v_pk_fma_f32 v[20:21], v[106:107], v[4:5], v[20:21] op_sel:[0,1,0]
	v_pk_mul_f32 v[22:23], v[116:117], v[120:121] op_sel_hi:[1,0]
	v_pk_mul_f32 v[24:25], v[118:119], v[120:121] op_sel_hi:[1,0]
	v_add_f32_dpp v26, v20, v20 row_ror:8 row_mask:0xf bank_mask:0xf bound_ctrl:1
	v_add_f32_dpp v28, v21, v21 row_ror:8 row_mask:0xf bank_mask:0xf bound_ctrl:1
	v_pk_fma_f32 v[22:23], v[2:3], v[108:109], v[22:23]
	v_add_f32_dpp v26, v26, v26 row_ror:4 row_mask:0xf bank_mask:0xf bound_ctrl:1
	v_pk_fma_f32 v[24:25], v[4:5], v[110:111], v[24:25]
	v_add_f32_dpp v28, v28, v28 row_ror:4 row_mask:0xf bank_mask:0xf bound_ctrl:1
	v_add_f32_dpp v26, v26, v26 row_ror:2 row_mask:0xf bank_mask:0xf bound_ctrl:1
	ds_read_b32 v200, v18 offset:12288
	ds_read_b64 v[202:203], v19 offset:12352
	v_add_f32_dpp v26, v26, v26 row_ror:1 row_mask:0xf bank_mask:0xf bound_ctrl:1
	v_pk_fma_f32 v[2:3], v[112:113], v[26:27], v[22:23] op_sel_hi:[1,0,1]
	v_pk_fma_f32 v[4:5], v[114:115], v[26:27], v[24:25] op_sel_hi:[1,0,1]
	v_fmac_f32_e32 v28, v122, v26
	v_fmac_f32_e32 v28, v120, v123
	ds_write_b32 v9, v28 offset:384
	s_waitcnt lgkmcnt(9)
	ds_read_b128 v[100:103], v17 offset:12384
	ds_read_b128 v[104:107], v17 offset:12640
	ds_read_b128 v[116:119], v17 offset:13408
	ds_read_b128 v[108:111], v17 offset:12896
	ds_read_b128 v[112:115], v17 offset:13152
	v_pk_mul_f32 v[20:21], v[2:3], v[156:157] op_sel_hi:[0,1]
	v_pk_fma_f32 v[20:21], v[158:159], v[2:3], v[20:21] op_sel:[0,1,0]
	v_pk_fma_f32 v[20:21], v[160:161], v[4:5], v[20:21] op_sel_hi:[1,0,1]
	v_pk_fma_f32 v[20:21], v[162:163], v[4:5], v[20:21] op_sel:[0,1,0]
	v_pk_mul_f32 v[22:23], v[172:173], v[176:177] op_sel_hi:[1,0]
	v_pk_mul_f32 v[24:25], v[174:175], v[176:177] op_sel_hi:[1,0]
	v_add_f32_dpp v26, v20, v20 row_ror:8 row_mask:0xf bank_mask:0xf bound_ctrl:1
	v_add_f32_dpp v28, v21, v21 row_ror:8 row_mask:0xf bank_mask:0xf bound_ctrl:1
	v_pk_fma_f32 v[22:23], v[2:3], v[164:165], v[22:23]
	v_add_f32_dpp v26, v26, v26 row_ror:4 row_mask:0xf bank_mask:0xf bound_ctrl:1
	v_pk_fma_f32 v[24:25], v[4:5], v[166:167], v[24:25]
	v_add_f32_dpp v28, v28, v28 row_ror:4 row_mask:0xf bank_mask:0xf bound_ctrl:1
	v_add_f32_dpp v26, v26, v26 row_ror:2 row_mask:0xf bank_mask:0xf bound_ctrl:1
	ds_read_b32 v120, v18 offset:13664
	ds_read_b64 v[122:123], v19 offset:13728
	v_add_f32_dpp v26, v26, v26 row_ror:1 row_mask:0xf bank_mask:0xf bound_ctrl:1
	v_pk_fma_f32 v[2:3], v[168:169], v[26:27], v[22:23] op_sel_hi:[1,0,1]
	v_pk_fma_f32 v[4:5], v[170:171], v[26:27], v[24:25] op_sel_hi:[1,0,1]
	v_fmac_f32_e32 v28, v178, v26
	v_fmac_f32_e32 v28, v176, v179
	ds_write_b32 v9, v28 offset:448
	s_waitcnt lgkmcnt(9)
	ds_read_b128 v[156:159], v17 offset:13760
	ds_read_b128 v[160:163], v17 offset:14016
	ds_read_b128 v[172:175], v17 offset:14784
	ds_read_b128 v[164:167], v17 offset:14272
	ds_read_b128 v[168:171], v17 offset:14528
	v_pk_mul_f32 v[20:21], v[2:3], v[180:181] op_sel_hi:[0,1]
	v_pk_fma_f32 v[20:21], v[182:183], v[2:3], v[20:21] op_sel:[0,1,0]
	v_pk_fma_f32 v[20:21], v[184:185], v[4:5], v[20:21] op_sel_hi:[1,0,1]
	v_pk_fma_f32 v[20:21], v[186:187], v[4:5], v[20:21] op_sel:[0,1,0]
	v_pk_mul_f32 v[22:23], v[196:197], v[200:201] op_sel_hi:[1,0]
	v_pk_mul_f32 v[24:25], v[198:199], v[200:201] op_sel_hi:[1,0]
	v_add_f32_dpp v26, v20, v20 row_ror:8 row_mask:0xf bank_mask:0xf bound_ctrl:1
	v_add_f32_dpp v28, v21, v21 row_ror:8 row_mask:0xf bank_mask:0xf bound_ctrl:1
	v_pk_fma_f32 v[22:23], v[2:3], v[188:189], v[22:23]
	v_add_f32_dpp v26, v26, v26 row_ror:4 row_mask:0xf bank_mask:0xf bound_ctrl:1
	v_pk_fma_f32 v[24:25], v[4:5], v[190:191], v[24:25]
	v_add_f32_dpp v28, v28, v28 row_ror:4 row_mask:0xf bank_mask:0xf bound_ctrl:1
	v_add_f32_dpp v26, v26, v26 row_ror:2 row_mask:0xf bank_mask:0xf bound_ctrl:1
	ds_read_b32 v176, v18 offset:15040
	ds_read_b64 v[178:179], v19 offset:15104
	v_add_f32_dpp v26, v26, v26 row_ror:1 row_mask:0xf bank_mask:0xf bound_ctrl:1
	v_pk_fma_f32 v[2:3], v[192:193], v[26:27], v[22:23] op_sel_hi:[1,0,1]
	v_pk_fma_f32 v[4:5], v[194:195], v[26:27], v[24:25] op_sel_hi:[1,0,1]
	v_fmac_f32_e32 v28, v202, v26
	v_fmac_f32_e32 v28, v200, v203
	ds_write_b32 v9, v28 offset:512
	s_waitcnt lgkmcnt(9)
	ds_read_b128 v[180:183], v17 offset:15136
	ds_read_b128 v[184:187], v17 offset:15392
	ds_read_b128 v[196:199], v17 offset:16160
	ds_read_b128 v[188:191], v17 offset:15648
	ds_read_b128 v[192:195], v17 offset:15904
	v_pk_mul_f32 v[20:21], v[2:3], v[100:101] op_sel_hi:[0,1]
	v_pk_fma_f32 v[20:21], v[102:103], v[2:3], v[20:21] op_sel:[0,1,0]
	v_pk_fma_f32 v[20:21], v[104:105], v[4:5], v[20:21] op_sel_hi:[1,0,1]
	v_pk_fma_f32 v[20:21], v[106:107], v[4:5], v[20:21] op_sel:[0,1,0]
	v_pk_mul_f32 v[22:23], v[116:117], v[120:121] op_sel_hi:[1,0]
	v_pk_mul_f32 v[24:25], v[118:119], v[120:121] op_sel_hi:[1,0]
	v_add_f32_dpp v26, v20, v20 row_ror:8 row_mask:0xf bank_mask:0xf bound_ctrl:1
	v_add_f32_dpp v28, v21, v21 row_ror:8 row_mask:0xf bank_mask:0xf bound_ctrl:1
	v_pk_fma_f32 v[22:23], v[2:3], v[108:109], v[22:23]
	v_add_f32_dpp v26, v26, v26 row_ror:4 row_mask:0xf bank_mask:0xf bound_ctrl:1
	v_pk_fma_f32 v[24:25], v[4:5], v[110:111], v[24:25]
	v_add_f32_dpp v28, v28, v28 row_ror:4 row_mask:0xf bank_mask:0xf bound_ctrl:1
	v_add_f32_dpp v26, v26, v26 row_ror:2 row_mask:0xf bank_mask:0xf bound_ctrl:1
	ds_read_b32 v200, v18 offset:16416
	ds_read_b64 v[202:203], v19 offset:16480
	v_add_f32_dpp v26, v26, v26 row_ror:1 row_mask:0xf bank_mask:0xf bound_ctrl:1
	v_pk_fma_f32 v[2:3], v[112:113], v[26:27], v[22:23] op_sel_hi:[1,0,1]
	v_pk_fma_f32 v[4:5], v[114:115], v[26:27], v[24:25] op_sel_hi:[1,0,1]
	v_fmac_f32_e32 v28, v122, v26
	v_fmac_f32_e32 v28, v120, v123
	ds_write_b32 v9, v28 offset:576
	s_waitcnt lgkmcnt(9)
	ds_read_b128 v[100:103], v17 offset:16512
	ds_read_b128 v[104:107], v17 offset:16768
	ds_read_b128 v[116:119], v17 offset:17536
	ds_read_b128 v[108:111], v17 offset:17024
	ds_read_b128 v[112:115], v17 offset:17280
	v_pk_mul_f32 v[20:21], v[2:3], v[156:157] op_sel_hi:[0,1]
	v_pk_fma_f32 v[20:21], v[158:159], v[2:3], v[20:21] op_sel:[0,1,0]
	v_pk_fma_f32 v[20:21], v[160:161], v[4:5], v[20:21] op_sel_hi:[1,0,1]
	v_pk_fma_f32 v[20:21], v[162:163], v[4:5], v[20:21] op_sel:[0,1,0]
	v_pk_mul_f32 v[22:23], v[172:173], v[176:177] op_sel_hi:[1,0]
	v_pk_mul_f32 v[24:25], v[174:175], v[176:177] op_sel_hi:[1,0]
	v_add_f32_dpp v26, v20, v20 row_ror:8 row_mask:0xf bank_mask:0xf bound_ctrl:1
	v_add_f32_dpp v28, v21, v21 row_ror:8 row_mask:0xf bank_mask:0xf bound_ctrl:1
	v_pk_fma_f32 v[22:23], v[2:3], v[164:165], v[22:23]
	v_add_f32_dpp v26, v26, v26 row_ror:4 row_mask:0xf bank_mask:0xf bound_ctrl:1
	v_pk_fma_f32 v[24:25], v[4:5], v[166:167], v[24:25]
	v_add_f32_dpp v28, v28, v28 row_ror:4 row_mask:0xf bank_mask:0xf bound_ctrl:1
	v_add_f32_dpp v26, v26, v26 row_ror:2 row_mask:0xf bank_mask:0xf bound_ctrl:1
	ds_read_b32 v120, v18 offset:17792
	ds_read_b64 v[122:123], v19 offset:17856
	v_add_f32_dpp v26, v26, v26 row_ror:1 row_mask:0xf bank_mask:0xf bound_ctrl:1
	v_pk_fma_f32 v[2:3], v[168:169], v[26:27], v[22:23] op_sel_hi:[1,0,1]
	v_pk_fma_f32 v[4:5], v[170:171], v[26:27], v[24:25] op_sel_hi:[1,0,1]
	v_fmac_f32_e32 v28, v178, v26
	v_fmac_f32_e32 v28, v176, v179
	ds_write_b32 v9, v28 offset:640
	s_waitcnt lgkmcnt(9)
	ds_read_b128 v[156:159], v17 offset:17888
	ds_read_b128 v[160:163], v17 offset:18144
	ds_read_b128 v[172:175], v17 offset:18912
	ds_read_b128 v[164:167], v17 offset:18400
	ds_read_b128 v[168:171], v17 offset:18656
	v_pk_mul_f32 v[20:21], v[2:3], v[180:181] op_sel_hi:[0,1]
	v_pk_fma_f32 v[20:21], v[182:183], v[2:3], v[20:21] op_sel:[0,1,0]
	v_pk_fma_f32 v[20:21], v[184:185], v[4:5], v[20:21] op_sel_hi:[1,0,1]
	v_pk_fma_f32 v[20:21], v[186:187], v[4:5], v[20:21] op_sel:[0,1,0]
	v_pk_mul_f32 v[22:23], v[196:197], v[200:201] op_sel_hi:[1,0]
	v_pk_mul_f32 v[24:25], v[198:199], v[200:201] op_sel_hi:[1,0]
	v_add_f32_dpp v26, v20, v20 row_ror:8 row_mask:0xf bank_mask:0xf bound_ctrl:1
	v_add_f32_dpp v28, v21, v21 row_ror:8 row_mask:0xf bank_mask:0xf bound_ctrl:1
	v_pk_fma_f32 v[22:23], v[2:3], v[188:189], v[22:23]
	v_add_f32_dpp v26, v26, v26 row_ror:4 row_mask:0xf bank_mask:0xf bound_ctrl:1
	v_pk_fma_f32 v[24:25], v[4:5], v[190:191], v[24:25]
	v_add_f32_dpp v28, v28, v28 row_ror:4 row_mask:0xf bank_mask:0xf bound_ctrl:1
	v_add_f32_dpp v26, v26, v26 row_ror:2 row_mask:0xf bank_mask:0xf bound_ctrl:1
	ds_read_b32 v176, v18 offset:19168
	ds_read_b64 v[178:179], v19 offset:19232
	v_add_f32_dpp v26, v26, v26 row_ror:1 row_mask:0xf bank_mask:0xf bound_ctrl:1
	v_pk_fma_f32 v[2:3], v[192:193], v[26:27], v[22:23] op_sel_hi:[1,0,1]
	v_pk_fma_f32 v[4:5], v[194:195], v[26:27], v[24:25] op_sel_hi:[1,0,1]
	v_fmac_f32_e32 v28, v202, v26
	v_fmac_f32_e32 v28, v200, v203
	ds_write_b32 v9, v28 offset:704
	s_waitcnt lgkmcnt(9)
	ds_read_b128 v[180:183], v17 offset:19264
	ds_read_b128 v[184:187], v17 offset:19520
	ds_read_b128 v[196:199], v17 offset:20288
	ds_read_b128 v[188:191], v17 offset:19776
	ds_read_b128 v[192:195], v17 offset:20032
	v_pk_mul_f32 v[20:21], v[2:3], v[100:101] op_sel_hi:[0,1]
	v_pk_fma_f32 v[20:21], v[102:103], v[2:3], v[20:21] op_sel:[0,1,0]
	v_pk_fma_f32 v[20:21], v[104:105], v[4:5], v[20:21] op_sel_hi:[1,0,1]
	v_pk_fma_f32 v[20:21], v[106:107], v[4:5], v[20:21] op_sel:[0,1,0]
	v_pk_mul_f32 v[22:23], v[116:117], v[120:121] op_sel_hi:[1,0]
	v_pk_mul_f32 v[24:25], v[118:119], v[120:121] op_sel_hi:[1,0]
	v_add_f32_dpp v26, v20, v20 row_ror:8 row_mask:0xf bank_mask:0xf bound_ctrl:1
	v_add_f32_dpp v28, v21, v21 row_ror:8 row_mask:0xf bank_mask:0xf bound_ctrl:1
	v_pk_fma_f32 v[22:23], v[2:3], v[108:109], v[22:23]
	v_add_f32_dpp v26, v26, v26 row_ror:4 row_mask:0xf bank_mask:0xf bound_ctrl:1
	v_pk_fma_f32 v[24:25], v[4:5], v[110:111], v[24:25]
	v_add_f32_dpp v28, v28, v28 row_ror:4 row_mask:0xf bank_mask:0xf bound_ctrl:1
	v_add_f32_dpp v26, v26, v26 row_ror:2 row_mask:0xf bank_mask:0xf bound_ctrl:1
	ds_read_b32 v200, v18 offset:20544
	ds_read_b64 v[202:203], v19 offset:20608
	v_add_f32_dpp v26, v26, v26 row_ror:1 row_mask:0xf bank_mask:0xf bound_ctrl:1
	v_pk_fma_f32 v[2:3], v[112:113], v[26:27], v[22:23] op_sel_hi:[1,0,1]
	v_pk_fma_f32 v[4:5], v[114:115], v[26:27], v[24:25] op_sel_hi:[1,0,1]
	v_fmac_f32_e32 v28, v122, v26
	v_fmac_f32_e32 v28, v120, v123
	ds_write_b32 v9, v28 offset:768
	s_waitcnt lgkmcnt(9)
	ds_read_b128 v[100:103], v17 offset:20640
	ds_read_b128 v[104:107], v17 offset:20896
	ds_read_b128 v[116:119], v17 offset:21664
	ds_read_b128 v[108:111], v17 offset:21152
	ds_read_b128 v[112:115], v17 offset:21408
	v_pk_mul_f32 v[20:21], v[2:3], v[156:157] op_sel_hi:[0,1]
	v_pk_fma_f32 v[20:21], v[158:159], v[2:3], v[20:21] op_sel:[0,1,0]
	v_pk_fma_f32 v[20:21], v[160:161], v[4:5], v[20:21] op_sel_hi:[1,0,1]
	v_pk_fma_f32 v[20:21], v[162:163], v[4:5], v[20:21] op_sel:[0,1,0]
	v_pk_mul_f32 v[22:23], v[172:173], v[176:177] op_sel_hi:[1,0]
	v_pk_mul_f32 v[24:25], v[174:175], v[176:177] op_sel_hi:[1,0]
	v_add_f32_dpp v26, v20, v20 row_ror:8 row_mask:0xf bank_mask:0xf bound_ctrl:1
	v_add_f32_dpp v28, v21, v21 row_ror:8 row_mask:0xf bank_mask:0xf bound_ctrl:1
	v_pk_fma_f32 v[22:23], v[2:3], v[164:165], v[22:23]
	v_add_f32_dpp v26, v26, v26 row_ror:4 row_mask:0xf bank_mask:0xf bound_ctrl:1
	v_pk_fma_f32 v[24:25], v[4:5], v[166:167], v[24:25]
	v_add_f32_dpp v28, v28, v28 row_ror:4 row_mask:0xf bank_mask:0xf bound_ctrl:1
	v_add_f32_dpp v26, v26, v26 row_ror:2 row_mask:0xf bank_mask:0xf bound_ctrl:1
	ds_read_b32 v120, v18 offset:21920
	ds_read_b64 v[122:123], v19 offset:21984
	v_add_f32_dpp v26, v26, v26 row_ror:1 row_mask:0xf bank_mask:0xf bound_ctrl:1
	v_pk_fma_f32 v[2:3], v[168:169], v[26:27], v[22:23] op_sel_hi:[1,0,1]
	v_pk_fma_f32 v[4:5], v[170:171], v[26:27], v[24:25] op_sel_hi:[1,0,1]
	v_fmac_f32_e32 v28, v178, v26
	v_fmac_f32_e32 v28, v176, v179
	ds_write_b32 v9, v28 offset:832
	s_waitcnt lgkmcnt(9)
	ds_read_b128 v[156:159], v17 offset:22016
	ds_read_b128 v[160:163], v17 offset:22272
	ds_read_b128 v[172:175], v17 offset:23040
	ds_read_b128 v[164:167], v17 offset:22528
	ds_read_b128 v[168:171], v17 offset:22784
	v_pk_mul_f32 v[20:21], v[2:3], v[180:181] op_sel_hi:[0,1]
	v_pk_fma_f32 v[20:21], v[182:183], v[2:3], v[20:21] op_sel:[0,1,0]
	v_pk_fma_f32 v[20:21], v[184:185], v[4:5], v[20:21] op_sel_hi:[1,0,1]
	v_pk_fma_f32 v[20:21], v[186:187], v[4:5], v[20:21] op_sel:[0,1,0]
	v_pk_mul_f32 v[22:23], v[196:197], v[200:201] op_sel_hi:[1,0]
	v_pk_mul_f32 v[24:25], v[198:199], v[200:201] op_sel_hi:[1,0]
	v_add_f32_dpp v26, v20, v20 row_ror:8 row_mask:0xf bank_mask:0xf bound_ctrl:1
	v_add_f32_dpp v28, v21, v21 row_ror:8 row_mask:0xf bank_mask:0xf bound_ctrl:1
	v_pk_fma_f32 v[22:23], v[2:3], v[188:189], v[22:23]
	v_add_f32_dpp v26, v26, v26 row_ror:4 row_mask:0xf bank_mask:0xf bound_ctrl:1
	v_pk_fma_f32 v[24:25], v[4:5], v[190:191], v[24:25]
	v_add_f32_dpp v28, v28, v28 row_ror:4 row_mask:0xf bank_mask:0xf bound_ctrl:1
	v_add_f32_dpp v26, v26, v26 row_ror:2 row_mask:0xf bank_mask:0xf bound_ctrl:1
	ds_read_b32 v176, v18 offset:23296
	ds_read_b64 v[178:179], v19 offset:23360
	v_add_f32_dpp v26, v26, v26 row_ror:1 row_mask:0xf bank_mask:0xf bound_ctrl:1
	v_pk_fma_f32 v[2:3], v[192:193], v[26:27], v[22:23] op_sel_hi:[1,0,1]
	v_pk_fma_f32 v[4:5], v[194:195], v[26:27], v[24:25] op_sel_hi:[1,0,1]
	v_fmac_f32_e32 v28, v202, v26
	v_fmac_f32_e32 v28, v200, v203
	ds_write_b32 v9, v28 offset:896
	s_waitcnt lgkmcnt(9)
	ds_read_b128 v[180:183], v17 offset:23392
	ds_read_b128 v[184:187], v17 offset:23648
	ds_read_b128 v[196:199], v17 offset:24416
	ds_read_b128 v[188:191], v17 offset:23904
	ds_read_b128 v[192:195], v17 offset:24160
	v_pk_mul_f32 v[20:21], v[2:3], v[100:101] op_sel_hi:[0,1]
	v_pk_fma_f32 v[20:21], v[102:103], v[2:3], v[20:21] op_sel:[0,1,0]
	v_pk_fma_f32 v[20:21], v[104:105], v[4:5], v[20:21] op_sel_hi:[1,0,1]
	v_pk_fma_f32 v[20:21], v[106:107], v[4:5], v[20:21] op_sel:[0,1,0]
	v_pk_mul_f32 v[22:23], v[116:117], v[120:121] op_sel_hi:[1,0]
	v_pk_mul_f32 v[24:25], v[118:119], v[120:121] op_sel_hi:[1,0]
	v_add_f32_dpp v26, v20, v20 row_ror:8 row_mask:0xf bank_mask:0xf bound_ctrl:1
	v_add_f32_dpp v28, v21, v21 row_ror:8 row_mask:0xf bank_mask:0xf bound_ctrl:1
	v_pk_fma_f32 v[22:23], v[2:3], v[108:109], v[22:23]
	v_add_f32_dpp v26, v26, v26 row_ror:4 row_mask:0xf bank_mask:0xf bound_ctrl:1
	v_pk_fma_f32 v[24:25], v[4:5], v[110:111], v[24:25]
	v_add_f32_dpp v28, v28, v28 row_ror:4 row_mask:0xf bank_mask:0xf bound_ctrl:1
	v_add_f32_dpp v26, v26, v26 row_ror:2 row_mask:0xf bank_mask:0xf bound_ctrl:1
	ds_read_b32 v200, v18 offset:24672
	ds_read_b64 v[202:203], v19 offset:24736
	v_add_f32_dpp v26, v26, v26 row_ror:1 row_mask:0xf bank_mask:0xf bound_ctrl:1
	v_pk_fma_f32 v[2:3], v[112:113], v[26:27], v[22:23] op_sel_hi:[1,0,1]
	v_pk_fma_f32 v[4:5], v[114:115], v[26:27], v[24:25] op_sel_hi:[1,0,1]
	v_fmac_f32_e32 v28, v122, v26
	v_fmac_f32_e32 v28, v120, v123
	ds_write_b32 v9, v28 offset:960
	s_waitcnt lgkmcnt(9)
	ds_read_b128 v[100:103], v17 offset:24768
	ds_read_b128 v[104:107], v17 offset:25024
	ds_read_b128 v[116:119], v17 offset:25792
	ds_read_b128 v[108:111], v17 offset:25280
	ds_read_b128 v[112:115], v17 offset:25536
	v_pk_mul_f32 v[20:21], v[2:3], v[156:157] op_sel_hi:[0,1]
	v_pk_fma_f32 v[20:21], v[158:159], v[2:3], v[20:21] op_sel:[0,1,0]
	v_pk_fma_f32 v[20:21], v[160:161], v[4:5], v[20:21] op_sel_hi:[1,0,1]
	v_pk_fma_f32 v[20:21], v[162:163], v[4:5], v[20:21] op_sel:[0,1,0]
	v_pk_mul_f32 v[22:23], v[172:173], v[176:177] op_sel_hi:[1,0]
	v_pk_mul_f32 v[24:25], v[174:175], v[176:177] op_sel_hi:[1,0]
	v_add_f32_dpp v26, v20, v20 row_ror:8 row_mask:0xf bank_mask:0xf bound_ctrl:1
	v_add_f32_dpp v28, v21, v21 row_ror:8 row_mask:0xf bank_mask:0xf bound_ctrl:1
	v_pk_fma_f32 v[22:23], v[2:3], v[164:165], v[22:23]
	v_add_f32_dpp v26, v26, v26 row_ror:4 row_mask:0xf bank_mask:0xf bound_ctrl:1
	v_pk_fma_f32 v[24:25], v[4:5], v[166:167], v[24:25]
	v_add_f32_dpp v28, v28, v28 row_ror:4 row_mask:0xf bank_mask:0xf bound_ctrl:1
	v_add_f32_dpp v26, v26, v26 row_ror:2 row_mask:0xf bank_mask:0xf bound_ctrl:1
	ds_read_b32 v120, v18 offset:26048
	ds_read_b64 v[122:123], v19 offset:26112
	v_add_f32_dpp v26, v26, v26 row_ror:1 row_mask:0xf bank_mask:0xf bound_ctrl:1
	v_pk_fma_f32 v[2:3], v[168:169], v[26:27], v[22:23] op_sel_hi:[1,0,1]
	v_pk_fma_f32 v[4:5], v[170:171], v[26:27], v[24:25] op_sel_hi:[1,0,1]
	v_fmac_f32_e32 v28, v178, v26
	v_fmac_f32_e32 v28, v176, v179
	ds_write_b32 v9, v28 offset:1024
	s_waitcnt lgkmcnt(9)
	ds_read_b128 v[156:159], v17 offset:26144
	ds_read_b128 v[160:163], v17 offset:26400
	ds_read_b128 v[172:175], v17 offset:27168
	ds_read_b128 v[164:167], v17 offset:26656
	ds_read_b128 v[168:171], v17 offset:26912
	v_pk_mul_f32 v[20:21], v[2:3], v[180:181] op_sel_hi:[0,1]
	v_pk_fma_f32 v[20:21], v[182:183], v[2:3], v[20:21] op_sel:[0,1,0]
	v_pk_fma_f32 v[20:21], v[184:185], v[4:5], v[20:21] op_sel_hi:[1,0,1]
	v_pk_fma_f32 v[20:21], v[186:187], v[4:5], v[20:21] op_sel:[0,1,0]
	v_pk_mul_f32 v[22:23], v[196:197], v[200:201] op_sel_hi:[1,0]
	v_pk_mul_f32 v[24:25], v[198:199], v[200:201] op_sel_hi:[1,0]
	v_add_f32_dpp v26, v20, v20 row_ror:8 row_mask:0xf bank_mask:0xf bound_ctrl:1
	v_add_f32_dpp v28, v21, v21 row_ror:8 row_mask:0xf bank_mask:0xf bound_ctrl:1
	v_pk_fma_f32 v[22:23], v[2:3], v[188:189], v[22:23]
	v_add_f32_dpp v26, v26, v26 row_ror:4 row_mask:0xf bank_mask:0xf bound_ctrl:1
	v_pk_fma_f32 v[24:25], v[4:5], v[190:191], v[24:25]
	v_add_f32_dpp v28, v28, v28 row_ror:4 row_mask:0xf bank_mask:0xf bound_ctrl:1
	v_add_f32_dpp v26, v26, v26 row_ror:2 row_mask:0xf bank_mask:0xf bound_ctrl:1
	ds_read_b32 v176, v18 offset:27424
	ds_read_b64 v[178:179], v19 offset:27488
	v_add_f32_dpp v26, v26, v26 row_ror:1 row_mask:0xf bank_mask:0xf bound_ctrl:1
	v_pk_fma_f32 v[2:3], v[192:193], v[26:27], v[22:23] op_sel_hi:[1,0,1]
	v_pk_fma_f32 v[4:5], v[194:195], v[26:27], v[24:25] op_sel_hi:[1,0,1]
	v_fmac_f32_e32 v28, v202, v26
	v_fmac_f32_e32 v28, v200, v203
	ds_write_b32 v9, v28 offset:1088
	s_waitcnt lgkmcnt(9)
	ds_read_b128 v[180:183], v17 offset:27520
	ds_read_b128 v[184:187], v17 offset:27776
	ds_read_b128 v[196:199], v17 offset:28544
	ds_read_b128 v[188:191], v17 offset:28032
	ds_read_b128 v[192:195], v17 offset:28288
	v_pk_mul_f32 v[20:21], v[2:3], v[100:101] op_sel_hi:[0,1]
	v_pk_fma_f32 v[20:21], v[102:103], v[2:3], v[20:21] op_sel:[0,1,0]
	v_pk_fma_f32 v[20:21], v[104:105], v[4:5], v[20:21] op_sel_hi:[1,0,1]
	v_pk_fma_f32 v[20:21], v[106:107], v[4:5], v[20:21] op_sel:[0,1,0]
	v_pk_mul_f32 v[22:23], v[116:117], v[120:121] op_sel_hi:[1,0]
	v_pk_mul_f32 v[24:25], v[118:119], v[120:121] op_sel_hi:[1,0]
	v_add_f32_dpp v26, v20, v20 row_ror:8 row_mask:0xf bank_mask:0xf bound_ctrl:1
	v_add_f32_dpp v28, v21, v21 row_ror:8 row_mask:0xf bank_mask:0xf bound_ctrl:1
	v_pk_fma_f32 v[22:23], v[2:3], v[108:109], v[22:23]
	v_add_f32_dpp v26, v26, v26 row_ror:4 row_mask:0xf bank_mask:0xf bound_ctrl:1
	v_pk_fma_f32 v[24:25], v[4:5], v[110:111], v[24:25]
	v_add_f32_dpp v28, v28, v28 row_ror:4 row_mask:0xf bank_mask:0xf bound_ctrl:1
	v_add_f32_dpp v26, v26, v26 row_ror:2 row_mask:0xf bank_mask:0xf bound_ctrl:1
	ds_read_b32 v200, v18 offset:28800
	ds_read_b64 v[202:203], v19 offset:28864
	v_add_f32_dpp v26, v26, v26 row_ror:1 row_mask:0xf bank_mask:0xf bound_ctrl:1
	v_pk_fma_f32 v[2:3], v[112:113], v[26:27], v[22:23] op_sel_hi:[1,0,1]
	v_pk_fma_f32 v[4:5], v[114:115], v[26:27], v[24:25] op_sel_hi:[1,0,1]
	v_fmac_f32_e32 v28, v122, v26
	v_fmac_f32_e32 v28, v120, v123
	ds_write_b32 v9, v28 offset:1152
	s_waitcnt lgkmcnt(9)
	ds_read_b128 v[100:103], v17 offset:28896
	ds_read_b128 v[104:107], v17 offset:29152
	ds_read_b128 v[116:119], v17 offset:29920
	ds_read_b128 v[108:111], v17 offset:29408
	ds_read_b128 v[112:115], v17 offset:29664
	v_pk_mul_f32 v[20:21], v[2:3], v[156:157] op_sel_hi:[0,1]
	v_pk_fma_f32 v[20:21], v[158:159], v[2:3], v[20:21] op_sel:[0,1,0]
	v_pk_fma_f32 v[20:21], v[160:161], v[4:5], v[20:21] op_sel_hi:[1,0,1]
	v_pk_fma_f32 v[20:21], v[162:163], v[4:5], v[20:21] op_sel:[0,1,0]
	v_pk_mul_f32 v[22:23], v[172:173], v[176:177] op_sel_hi:[1,0]
	v_pk_mul_f32 v[24:25], v[174:175], v[176:177] op_sel_hi:[1,0]
	v_add_f32_dpp v26, v20, v20 row_ror:8 row_mask:0xf bank_mask:0xf bound_ctrl:1
	v_add_f32_dpp v28, v21, v21 row_ror:8 row_mask:0xf bank_mask:0xf bound_ctrl:1
	v_pk_fma_f32 v[22:23], v[2:3], v[164:165], v[22:23]
	v_add_f32_dpp v26, v26, v26 row_ror:4 row_mask:0xf bank_mask:0xf bound_ctrl:1
	v_pk_fma_f32 v[24:25], v[4:5], v[166:167], v[24:25]
	v_add_f32_dpp v28, v28, v28 row_ror:4 row_mask:0xf bank_mask:0xf bound_ctrl:1
	v_add_f32_dpp v26, v26, v26 row_ror:2 row_mask:0xf bank_mask:0xf bound_ctrl:1
	ds_read_b32 v120, v18 offset:30176
	ds_read_b64 v[122:123], v19 offset:30240
	v_add_f32_dpp v26, v26, v26 row_ror:1 row_mask:0xf bank_mask:0xf bound_ctrl:1
	v_pk_fma_f32 v[2:3], v[168:169], v[26:27], v[22:23] op_sel_hi:[1,0,1]
	v_pk_fma_f32 v[4:5], v[170:171], v[26:27], v[24:25] op_sel_hi:[1,0,1]
	v_fmac_f32_e32 v28, v178, v26
	v_fmac_f32_e32 v28, v176, v179
	ds_write_b32 v9, v28 offset:1216
	s_waitcnt lgkmcnt(9)
	ds_read_b128 v[156:159], v17 offset:30272
	ds_read_b128 v[160:163], v17 offset:30528
	ds_read_b128 v[172:175], v17 offset:31296
	ds_read_b128 v[164:167], v17 offset:30784
	ds_read_b128 v[168:171], v17 offset:31040
	v_pk_mul_f32 v[20:21], v[2:3], v[180:181] op_sel_hi:[0,1]
	v_pk_fma_f32 v[20:21], v[182:183], v[2:3], v[20:21] op_sel:[0,1,0]
	v_pk_fma_f32 v[20:21], v[184:185], v[4:5], v[20:21] op_sel_hi:[1,0,1]
	v_pk_fma_f32 v[20:21], v[186:187], v[4:5], v[20:21] op_sel:[0,1,0]
	v_pk_mul_f32 v[22:23], v[196:197], v[200:201] op_sel_hi:[1,0]
	v_pk_mul_f32 v[24:25], v[198:199], v[200:201] op_sel_hi:[1,0]
	v_add_f32_dpp v26, v20, v20 row_ror:8 row_mask:0xf bank_mask:0xf bound_ctrl:1
	v_add_f32_dpp v28, v21, v21 row_ror:8 row_mask:0xf bank_mask:0xf bound_ctrl:1
	v_pk_fma_f32 v[22:23], v[2:3], v[188:189], v[22:23]
	v_add_f32_dpp v26, v26, v26 row_ror:4 row_mask:0xf bank_mask:0xf bound_ctrl:1
	v_pk_fma_f32 v[24:25], v[4:5], v[190:191], v[24:25]
	v_add_f32_dpp v28, v28, v28 row_ror:4 row_mask:0xf bank_mask:0xf bound_ctrl:1
	v_add_f32_dpp v26, v26, v26 row_ror:2 row_mask:0xf bank_mask:0xf bound_ctrl:1
	ds_read_b32 v176, v18 offset:31552
	ds_read_b64 v[178:179], v19 offset:31616
	v_add_f32_dpp v26, v26, v26 row_ror:1 row_mask:0xf bank_mask:0xf bound_ctrl:1
	v_pk_fma_f32 v[2:3], v[192:193], v[26:27], v[22:23] op_sel_hi:[1,0,1]
	v_pk_fma_f32 v[4:5], v[194:195], v[26:27], v[24:25] op_sel_hi:[1,0,1]
	v_fmac_f32_e32 v28, v202, v26
	v_fmac_f32_e32 v28, v200, v203
	ds_write_b32 v9, v28 offset:1280
	s_waitcnt lgkmcnt(9)
	ds_read_b128 v[180:183], v17 offset:31648
	ds_read_b128 v[184:187], v17 offset:31904
	ds_read_b128 v[196:199], v17 offset:32672
	ds_read_b128 v[188:191], v17 offset:32160
	ds_read_b128 v[192:195], v17 offset:32416
	v_pk_mul_f32 v[20:21], v[2:3], v[100:101] op_sel_hi:[0,1]
	v_pk_fma_f32 v[20:21], v[102:103], v[2:3], v[20:21] op_sel:[0,1,0]
	v_pk_fma_f32 v[20:21], v[104:105], v[4:5], v[20:21] op_sel_hi:[1,0,1]
	v_pk_fma_f32 v[20:21], v[106:107], v[4:5], v[20:21] op_sel:[0,1,0]
	v_pk_mul_f32 v[22:23], v[116:117], v[120:121] op_sel_hi:[1,0]
	v_pk_mul_f32 v[24:25], v[118:119], v[120:121] op_sel_hi:[1,0]
	v_add_f32_dpp v26, v20, v20 row_ror:8 row_mask:0xf bank_mask:0xf bound_ctrl:1
	v_add_f32_dpp v28, v21, v21 row_ror:8 row_mask:0xf bank_mask:0xf bound_ctrl:1
	v_pk_fma_f32 v[22:23], v[2:3], v[108:109], v[22:23]
	v_add_f32_dpp v26, v26, v26 row_ror:4 row_mask:0xf bank_mask:0xf bound_ctrl:1
	v_pk_fma_f32 v[24:25], v[4:5], v[110:111], v[24:25]
	v_add_f32_dpp v28, v28, v28 row_ror:4 row_mask:0xf bank_mask:0xf bound_ctrl:1
	v_add_f32_dpp v26, v26, v26 row_ror:2 row_mask:0xf bank_mask:0xf bound_ctrl:1
	ds_read_b32 v200, v18 offset:32928
	ds_read_b64 v[202:203], v19 offset:32992
	v_add_f32_dpp v26, v26, v26 row_ror:1 row_mask:0xf bank_mask:0xf bound_ctrl:1
	v_pk_fma_f32 v[2:3], v[112:113], v[26:27], v[22:23] op_sel_hi:[1,0,1]
	v_pk_fma_f32 v[4:5], v[114:115], v[26:27], v[24:25] op_sel_hi:[1,0,1]
	v_fmac_f32_e32 v28, v122, v26
	v_fmac_f32_e32 v28, v120, v123
	ds_write_b32 v9, v28 offset:1344
	s_waitcnt lgkmcnt(9)
	ds_read_b128 v[100:103], v17 offset:33024
	ds_read_b128 v[104:107], v17 offset:33280
	ds_read_b128 v[116:119], v17 offset:34048
	ds_read_b128 v[108:111], v17 offset:33536
	ds_read_b128 v[112:115], v17 offset:33792
	v_pk_mul_f32 v[20:21], v[2:3], v[156:157] op_sel_hi:[0,1]
	v_pk_fma_f32 v[20:21], v[158:159], v[2:3], v[20:21] op_sel:[0,1,0]
	v_pk_fma_f32 v[20:21], v[160:161], v[4:5], v[20:21] op_sel_hi:[1,0,1]
	v_pk_fma_f32 v[20:21], v[162:163], v[4:5], v[20:21] op_sel:[0,1,0]
	v_pk_mul_f32 v[22:23], v[172:173], v[176:177] op_sel_hi:[1,0]
	v_pk_mul_f32 v[24:25], v[174:175], v[176:177] op_sel_hi:[1,0]
	v_add_f32_dpp v26, v20, v20 row_ror:8 row_mask:0xf bank_mask:0xf bound_ctrl:1
	v_add_f32_dpp v28, v21, v21 row_ror:8 row_mask:0xf bank_mask:0xf bound_ctrl:1
	v_pk_fma_f32 v[22:23], v[2:3], v[164:165], v[22:23]
	v_add_f32_dpp v26, v26, v26 row_ror:4 row_mask:0xf bank_mask:0xf bound_ctrl:1
	v_pk_fma_f32 v[24:25], v[4:5], v[166:167], v[24:25]
	v_add_f32_dpp v28, v28, v28 row_ror:4 row_mask:0xf bank_mask:0xf bound_ctrl:1
	v_add_f32_dpp v26, v26, v26 row_ror:2 row_mask:0xf bank_mask:0xf bound_ctrl:1
	ds_read_b32 v120, v18 offset:34304
	ds_read_b64 v[122:123], v19 offset:34368
	v_add_f32_dpp v26, v26, v26 row_ror:1 row_mask:0xf bank_mask:0xf bound_ctrl:1
	v_pk_fma_f32 v[2:3], v[168:169], v[26:27], v[22:23] op_sel_hi:[1,0,1]
	v_pk_fma_f32 v[4:5], v[170:171], v[26:27], v[24:25] op_sel_hi:[1,0,1]
	v_fmac_f32_e32 v28, v178, v26
	v_fmac_f32_e32 v28, v176, v179
	ds_write_b32 v9, v28 offset:1408
	s_waitcnt lgkmcnt(9)
	ds_read_b128 v[156:159], v17 offset:34400
	ds_read_b128 v[160:163], v17 offset:34656
	ds_read_b128 v[172:175], v17 offset:35424
	ds_read_b128 v[164:167], v17 offset:34912
	ds_read_b128 v[168:171], v17 offset:35168
	v_pk_mul_f32 v[20:21], v[2:3], v[180:181] op_sel_hi:[0,1]
	v_pk_fma_f32 v[20:21], v[182:183], v[2:3], v[20:21] op_sel:[0,1,0]
	v_pk_fma_f32 v[20:21], v[184:185], v[4:5], v[20:21] op_sel_hi:[1,0,1]
	v_pk_fma_f32 v[20:21], v[186:187], v[4:5], v[20:21] op_sel:[0,1,0]
	v_pk_mul_f32 v[22:23], v[196:197], v[200:201] op_sel_hi:[1,0]
	v_pk_mul_f32 v[24:25], v[198:199], v[200:201] op_sel_hi:[1,0]
	v_add_f32_dpp v26, v20, v20 row_ror:8 row_mask:0xf bank_mask:0xf bound_ctrl:1
	v_add_f32_dpp v28, v21, v21 row_ror:8 row_mask:0xf bank_mask:0xf bound_ctrl:1
	v_pk_fma_f32 v[22:23], v[2:3], v[188:189], v[22:23]
	v_add_f32_dpp v26, v26, v26 row_ror:4 row_mask:0xf bank_mask:0xf bound_ctrl:1
	v_pk_fma_f32 v[24:25], v[4:5], v[190:191], v[24:25]
	v_add_f32_dpp v28, v28, v28 row_ror:4 row_mask:0xf bank_mask:0xf bound_ctrl:1
	v_add_f32_dpp v26, v26, v26 row_ror:2 row_mask:0xf bank_mask:0xf bound_ctrl:1
	ds_read_b32 v176, v18 offset:35680
	ds_read_b64 v[178:179], v19 offset:35744
	v_add_f32_dpp v26, v26, v26 row_ror:1 row_mask:0xf bank_mask:0xf bound_ctrl:1
	v_pk_fma_f32 v[2:3], v[192:193], v[26:27], v[22:23] op_sel_hi:[1,0,1]
	v_pk_fma_f32 v[4:5], v[194:195], v[26:27], v[24:25] op_sel_hi:[1,0,1]
	v_fmac_f32_e32 v28, v202, v26
	v_fmac_f32_e32 v28, v200, v203
	ds_write_b32 v9, v28 offset:1472
	s_waitcnt lgkmcnt(9)
	ds_read_b128 v[180:183], v17 offset:35776
	ds_read_b128 v[184:187], v17 offset:36032
	ds_read_b128 v[196:199], v17 offset:36800
	ds_read_b128 v[188:191], v17 offset:36288
	ds_read_b128 v[192:195], v17 offset:36544
	v_pk_mul_f32 v[20:21], v[2:3], v[100:101] op_sel_hi:[0,1]
	v_pk_fma_f32 v[20:21], v[102:103], v[2:3], v[20:21] op_sel:[0,1,0]
	v_pk_fma_f32 v[20:21], v[104:105], v[4:5], v[20:21] op_sel_hi:[1,0,1]
	v_pk_fma_f32 v[20:21], v[106:107], v[4:5], v[20:21] op_sel:[0,1,0]
	v_pk_mul_f32 v[22:23], v[116:117], v[120:121] op_sel_hi:[1,0]
	v_pk_mul_f32 v[24:25], v[118:119], v[120:121] op_sel_hi:[1,0]
	v_add_f32_dpp v26, v20, v20 row_ror:8 row_mask:0xf bank_mask:0xf bound_ctrl:1
	v_add_f32_dpp v28, v21, v21 row_ror:8 row_mask:0xf bank_mask:0xf bound_ctrl:1
	v_pk_fma_f32 v[22:23], v[2:3], v[108:109], v[22:23]
	v_add_f32_dpp v26, v26, v26 row_ror:4 row_mask:0xf bank_mask:0xf bound_ctrl:1
	v_pk_fma_f32 v[24:25], v[4:5], v[110:111], v[24:25]
	v_add_f32_dpp v28, v28, v28 row_ror:4 row_mask:0xf bank_mask:0xf bound_ctrl:1
	v_add_f32_dpp v26, v26, v26 row_ror:2 row_mask:0xf bank_mask:0xf bound_ctrl:1
	ds_read_b32 v200, v18 offset:37056
	ds_read_b64 v[202:203], v19 offset:37120
	v_add_f32_dpp v26, v26, v26 row_ror:1 row_mask:0xf bank_mask:0xf bound_ctrl:1
	v_pk_fma_f32 v[2:3], v[112:113], v[26:27], v[22:23] op_sel_hi:[1,0,1]
	v_pk_fma_f32 v[4:5], v[114:115], v[26:27], v[24:25] op_sel_hi:[1,0,1]
	v_fmac_f32_e32 v28, v122, v26
	v_fmac_f32_e32 v28, v120, v123
	ds_write_b32 v9, v28 offset:1536
	s_waitcnt lgkmcnt(9)
	ds_read_b128 v[100:103], v17 offset:37152
	ds_read_b128 v[104:107], v17 offset:37408
	ds_read_b128 v[116:119], v17 offset:38176
	ds_read_b128 v[108:111], v17 offset:37664
	ds_read_b128 v[112:115], v17 offset:37920
	v_pk_mul_f32 v[20:21], v[2:3], v[156:157] op_sel_hi:[0,1]
	v_pk_fma_f32 v[20:21], v[158:159], v[2:3], v[20:21] op_sel:[0,1,0]
	v_pk_fma_f32 v[20:21], v[160:161], v[4:5], v[20:21] op_sel_hi:[1,0,1]
	v_pk_fma_f32 v[20:21], v[162:163], v[4:5], v[20:21] op_sel:[0,1,0]
	v_pk_mul_f32 v[22:23], v[172:173], v[176:177] op_sel_hi:[1,0]
	v_pk_mul_f32 v[24:25], v[174:175], v[176:177] op_sel_hi:[1,0]
	v_add_f32_dpp v26, v20, v20 row_ror:8 row_mask:0xf bank_mask:0xf bound_ctrl:1
	v_add_f32_dpp v28, v21, v21 row_ror:8 row_mask:0xf bank_mask:0xf bound_ctrl:1
	v_pk_fma_f32 v[22:23], v[2:3], v[164:165], v[22:23]
	v_add_f32_dpp v26, v26, v26 row_ror:4 row_mask:0xf bank_mask:0xf bound_ctrl:1
	v_pk_fma_f32 v[24:25], v[4:5], v[166:167], v[24:25]
	v_add_f32_dpp v28, v28, v28 row_ror:4 row_mask:0xf bank_mask:0xf bound_ctrl:1
	v_add_f32_dpp v26, v26, v26 row_ror:2 row_mask:0xf bank_mask:0xf bound_ctrl:1
	ds_read_b32 v120, v18 offset:38432
	ds_read_b64 v[122:123], v19 offset:38496
	v_add_f32_dpp v26, v26, v26 row_ror:1 row_mask:0xf bank_mask:0xf bound_ctrl:1
	v_pk_fma_f32 v[2:3], v[168:169], v[26:27], v[22:23] op_sel_hi:[1,0,1]
	v_pk_fma_f32 v[4:5], v[170:171], v[26:27], v[24:25] op_sel_hi:[1,0,1]
	v_fmac_f32_e32 v28, v178, v26
	v_fmac_f32_e32 v28, v176, v179
	ds_write_b32 v9, v28 offset:1600
	s_waitcnt lgkmcnt(9)
	ds_read_b128 v[156:159], v17 offset:38528
	ds_read_b128 v[160:163], v17 offset:38784
	ds_read_b128 v[172:175], v17 offset:39552
	ds_read_b128 v[164:167], v17 offset:39040
	ds_read_b128 v[168:171], v17 offset:39296
	v_pk_mul_f32 v[20:21], v[2:3], v[180:181] op_sel_hi:[0,1]
	v_pk_fma_f32 v[20:21], v[182:183], v[2:3], v[20:21] op_sel:[0,1,0]
	v_pk_fma_f32 v[20:21], v[184:185], v[4:5], v[20:21] op_sel_hi:[1,0,1]
	v_pk_fma_f32 v[20:21], v[186:187], v[4:5], v[20:21] op_sel:[0,1,0]
	v_pk_mul_f32 v[22:23], v[196:197], v[200:201] op_sel_hi:[1,0]
	v_pk_mul_f32 v[24:25], v[198:199], v[200:201] op_sel_hi:[1,0]
	v_add_f32_dpp v26, v20, v20 row_ror:8 row_mask:0xf bank_mask:0xf bound_ctrl:1
	v_add_f32_dpp v28, v21, v21 row_ror:8 row_mask:0xf bank_mask:0xf bound_ctrl:1
	v_pk_fma_f32 v[22:23], v[2:3], v[188:189], v[22:23]
	v_add_f32_dpp v26, v26, v26 row_ror:4 row_mask:0xf bank_mask:0xf bound_ctrl:1
	v_pk_fma_f32 v[24:25], v[4:5], v[190:191], v[24:25]
	v_add_f32_dpp v28, v28, v28 row_ror:4 row_mask:0xf bank_mask:0xf bound_ctrl:1
	v_add_f32_dpp v26, v26, v26 row_ror:2 row_mask:0xf bank_mask:0xf bound_ctrl:1
	ds_read_b32 v176, v18 offset:39808
	ds_read_b64 v[178:179], v19 offset:39872
	v_add_f32_dpp v26, v26, v26 row_ror:1 row_mask:0xf bank_mask:0xf bound_ctrl:1
	v_pk_fma_f32 v[2:3], v[192:193], v[26:27], v[22:23] op_sel_hi:[1,0,1]
	v_pk_fma_f32 v[4:5], v[194:195], v[26:27], v[24:25] op_sel_hi:[1,0,1]
	v_fmac_f32_e32 v28, v202, v26
	v_fmac_f32_e32 v28, v200, v203
	ds_write_b32 v9, v28 offset:1664
	s_waitcnt lgkmcnt(9)
	ds_read_b128 v[180:183], v17 offset:39904
	ds_read_b128 v[184:187], v17 offset:40160
	ds_read_b128 v[196:199], v17 offset:40928
	ds_read_b128 v[188:191], v17 offset:40416
	ds_read_b128 v[192:195], v17 offset:40672
	v_pk_mul_f32 v[20:21], v[2:3], v[100:101] op_sel_hi:[0,1]
	v_pk_fma_f32 v[20:21], v[102:103], v[2:3], v[20:21] op_sel:[0,1,0]
	v_pk_fma_f32 v[20:21], v[104:105], v[4:5], v[20:21] op_sel_hi:[1,0,1]
	v_pk_fma_f32 v[20:21], v[106:107], v[4:5], v[20:21] op_sel:[0,1,0]
	v_pk_mul_f32 v[22:23], v[116:117], v[120:121] op_sel_hi:[1,0]
	v_pk_mul_f32 v[24:25], v[118:119], v[120:121] op_sel_hi:[1,0]
	v_add_f32_dpp v26, v20, v20 row_ror:8 row_mask:0xf bank_mask:0xf bound_ctrl:1
	v_add_f32_dpp v28, v21, v21 row_ror:8 row_mask:0xf bank_mask:0xf bound_ctrl:1
	v_pk_fma_f32 v[22:23], v[2:3], v[108:109], v[22:23]
	v_add_f32_dpp v26, v26, v26 row_ror:4 row_mask:0xf bank_mask:0xf bound_ctrl:1
	v_pk_fma_f32 v[24:25], v[4:5], v[110:111], v[24:25]
	v_add_f32_dpp v28, v28, v28 row_ror:4 row_mask:0xf bank_mask:0xf bound_ctrl:1
	v_add_f32_dpp v26, v26, v26 row_ror:2 row_mask:0xf bank_mask:0xf bound_ctrl:1
	ds_read_b32 v200, v18 offset:41184
	ds_read_b64 v[202:203], v19 offset:41248
	v_add_f32_dpp v26, v26, v26 row_ror:1 row_mask:0xf bank_mask:0xf bound_ctrl:1
	v_pk_fma_f32 v[2:3], v[112:113], v[26:27], v[22:23] op_sel_hi:[1,0,1]
	v_pk_fma_f32 v[4:5], v[114:115], v[26:27], v[24:25] op_sel_hi:[1,0,1]
	v_fmac_f32_e32 v28, v122, v26
	v_fmac_f32_e32 v28, v120, v123
	ds_write_b32 v9, v28 offset:1728
	s_waitcnt lgkmcnt(9)
	ds_read_b128 v[100:103], v17 offset:41280
	ds_read_b128 v[104:107], v17 offset:41536
	ds_read_b128 v[116:119], v17 offset:42304
	ds_read_b128 v[108:111], v17 offset:41792
	ds_read_b128 v[112:115], v17 offset:42048
	v_pk_mul_f32 v[20:21], v[2:3], v[156:157] op_sel_hi:[0,1]
	v_pk_fma_f32 v[20:21], v[158:159], v[2:3], v[20:21] op_sel:[0,1,0]
	v_pk_fma_f32 v[20:21], v[160:161], v[4:5], v[20:21] op_sel_hi:[1,0,1]
	v_pk_fma_f32 v[20:21], v[162:163], v[4:5], v[20:21] op_sel:[0,1,0]
	v_pk_mul_f32 v[22:23], v[172:173], v[176:177] op_sel_hi:[1,0]
	v_pk_mul_f32 v[24:25], v[174:175], v[176:177] op_sel_hi:[1,0]
	v_add_f32_dpp v26, v20, v20 row_ror:8 row_mask:0xf bank_mask:0xf bound_ctrl:1
	v_add_f32_dpp v28, v21, v21 row_ror:8 row_mask:0xf bank_mask:0xf bound_ctrl:1
	v_pk_fma_f32 v[22:23], v[2:3], v[164:165], v[22:23]
	v_add_f32_dpp v26, v26, v26 row_ror:4 row_mask:0xf bank_mask:0xf bound_ctrl:1
	v_pk_fma_f32 v[24:25], v[4:5], v[166:167], v[24:25]
	v_add_f32_dpp v28, v28, v28 row_ror:4 row_mask:0xf bank_mask:0xf bound_ctrl:1
	v_add_f32_dpp v26, v26, v26 row_ror:2 row_mask:0xf bank_mask:0xf bound_ctrl:1
	ds_read_b32 v120, v18 offset:42560
	ds_read_b64 v[122:123], v19 offset:42624
	v_add_f32_dpp v26, v26, v26 row_ror:1 row_mask:0xf bank_mask:0xf bound_ctrl:1
	v_pk_fma_f32 v[2:3], v[168:169], v[26:27], v[22:23] op_sel_hi:[1,0,1]
	v_pk_fma_f32 v[4:5], v[170:171], v[26:27], v[24:25] op_sel_hi:[1,0,1]
	v_fmac_f32_e32 v28, v178, v26
	v_fmac_f32_e32 v28, v176, v179
	ds_write_b32 v9, v28 offset:1792
	s_waitcnt lgkmcnt(9)
	ds_read_b128 v[156:159], v17 offset:42656
	ds_read_b128 v[160:163], v17 offset:42912
	ds_read_b128 v[172:175], v17 offset:43680
	ds_read_b128 v[164:167], v17 offset:43168
	ds_read_b128 v[168:171], v17 offset:43424
	v_pk_mul_f32 v[20:21], v[2:3], v[180:181] op_sel_hi:[0,1]
	v_pk_fma_f32 v[20:21], v[182:183], v[2:3], v[20:21] op_sel:[0,1,0]
	v_pk_fma_f32 v[20:21], v[184:185], v[4:5], v[20:21] op_sel_hi:[1,0,1]
	v_pk_fma_f32 v[20:21], v[186:187], v[4:5], v[20:21] op_sel:[0,1,0]
	v_pk_mul_f32 v[22:23], v[196:197], v[200:201] op_sel_hi:[1,0]
	v_pk_mul_f32 v[24:25], v[198:199], v[200:201] op_sel_hi:[1,0]
	v_add_f32_dpp v26, v20, v20 row_ror:8 row_mask:0xf bank_mask:0xf bound_ctrl:1
	v_add_f32_dpp v28, v21, v21 row_ror:8 row_mask:0xf bank_mask:0xf bound_ctrl:1
	v_pk_fma_f32 v[22:23], v[2:3], v[188:189], v[22:23]
	v_add_f32_dpp v26, v26, v26 row_ror:4 row_mask:0xf bank_mask:0xf bound_ctrl:1
	v_pk_fma_f32 v[24:25], v[4:5], v[190:191], v[24:25]
	v_add_f32_dpp v28, v28, v28 row_ror:4 row_mask:0xf bank_mask:0xf bound_ctrl:1
	v_add_f32_dpp v26, v26, v26 row_ror:2 row_mask:0xf bank_mask:0xf bound_ctrl:1
	ds_read_b32 v176, v18 offset:43936
	ds_read_b64 v[178:179], v19 offset:44000
	v_add_f32_dpp v26, v26, v26 row_ror:1 row_mask:0xf bank_mask:0xf bound_ctrl:1
	v_pk_fma_f32 v[2:3], v[192:193], v[26:27], v[22:23] op_sel_hi:[1,0,1]
	v_pk_fma_f32 v[4:5], v[194:195], v[26:27], v[24:25] op_sel_hi:[1,0,1]
	v_fmac_f32_e32 v28, v202, v26
	v_fmac_f32_e32 v28, v200, v203
	ds_write_b32 v9, v28 offset:1856
	s_waitcnt lgkmcnt(9)
	v_pk_mul_f32 v[20:21], v[2:3], v[100:101] op_sel_hi:[0,1]
	v_pk_fma_f32 v[20:21], v[102:103], v[2:3], v[20:21] op_sel:[0,1,0]
	v_pk_fma_f32 v[20:21], v[104:105], v[4:5], v[20:21] op_sel_hi:[1,0,1]
	v_pk_fma_f32 v[20:21], v[106:107], v[4:5], v[20:21] op_sel:[0,1,0]
	v_pk_mul_f32 v[22:23], v[116:117], v[120:121] op_sel_hi:[1,0]
	v_pk_mul_f32 v[24:25], v[118:119], v[120:121] op_sel_hi:[1,0]
	v_add_f32_dpp v26, v20, v20 row_ror:8 row_mask:0xf bank_mask:0xf bound_ctrl:1
	v_add_f32_dpp v28, v21, v21 row_ror:8 row_mask:0xf bank_mask:0xf bound_ctrl:1
	v_pk_fma_f32 v[22:23], v[2:3], v[108:109], v[22:23]
	v_add_f32_dpp v26, v26, v26 row_ror:4 row_mask:0xf bank_mask:0xf bound_ctrl:1
	v_pk_fma_f32 v[24:25], v[4:5], v[110:111], v[24:25]
	v_add_f32_dpp v28, v28, v28 row_ror:4 row_mask:0xf bank_mask:0xf bound_ctrl:1
	v_add_f32_dpp v26, v26, v26 row_ror:2 row_mask:0xf bank_mask:0xf bound_ctrl:1
	s_nop 1
	v_add_f32_dpp v26, v26, v26 row_ror:1 row_mask:0xf bank_mask:0xf bound_ctrl:1
	v_pk_fma_f32 v[2:3], v[112:113], v[26:27], v[22:23] op_sel_hi:[1,0,1]
	v_pk_fma_f32 v[4:5], v[114:115], v[26:27], v[24:25] op_sel_hi:[1,0,1]
	v_fmac_f32_e32 v28, v122, v26
	v_fmac_f32_e32 v28, v120, v123
	ds_write_b32 v9, v28 offset:1920
	s_waitcnt lgkmcnt(2)
	v_pk_mul_f32 v[20:21], v[2:3], v[156:157] op_sel_hi:[0,1]
	v_pk_fma_f32 v[20:21], v[158:159], v[2:3], v[20:21] op_sel:[0,1,0]
	v_pk_fma_f32 v[20:21], v[160:161], v[4:5], v[20:21] op_sel_hi:[1,0,1]
	v_pk_fma_f32 v[20:21], v[162:163], v[4:5], v[20:21] op_sel:[0,1,0]
	v_pk_mul_f32 v[22:23], v[172:173], v[176:177] op_sel_hi:[1,0]
	v_pk_mul_f32 v[24:25], v[174:175], v[176:177] op_sel_hi:[1,0]
	v_add_f32_dpp v26, v20, v20 row_ror:8 row_mask:0xf bank_mask:0xf bound_ctrl:1
	v_add_f32_dpp v28, v21, v21 row_ror:8 row_mask:0xf bank_mask:0xf bound_ctrl:1
	v_pk_fma_f32 v[22:23], v[2:3], v[164:165], v[22:23]
	v_add_f32_dpp v26, v26, v26 row_ror:4 row_mask:0xf bank_mask:0xf bound_ctrl:1
	v_pk_fma_f32 v[24:25], v[4:5], v[166:167], v[24:25]
	v_add_f32_dpp v28, v28, v28 row_ror:4 row_mask:0xf bank_mask:0xf bound_ctrl:1
	v_add_f32_dpp v26, v26, v26 row_ror:2 row_mask:0xf bank_mask:0xf bound_ctrl:1
	s_nop 1
	v_add_f32_dpp v26, v26, v26 row_ror:1 row_mask:0xf bank_mask:0xf bound_ctrl:1
	v_pk_fma_f32 v[2:3], v[168:169], v[26:27], v[22:23] op_sel_hi:[1,0,1]
	v_pk_fma_f32 v[4:5], v[170:171], v[26:27], v[24:25] op_sel_hi:[1,0,1]
	v_fmac_f32_e32 v28, v178, v26
	v_fmac_f32_e32 v28, v176, v179
	ds_write_b32 v9, v28 offset:1984
	ds_read_b128 v[30:33], v13
	ds_read_b128 v[34:37], v13 offset:16
	s_add_i32 s4, s4, 32
	s_waitcnt lgkmcnt(0)
	v_add_f32_e32 v38, v30, v31
	v_add_f32_e32 v39, v32, v33
	v_add_f32_e32 v40, v34, v35
	v_add_f32_e32 v41, v36, v37
	v_add_f32_e32 v38, v38, v39
	v_add_f32_e32 v40, v40, v41
	v_cvt_pk_bf16_f32 v6, v38, v40
	global_store_dword v[0:1], v6, off
	v_lshl_add_u64 v[0:1], v[0:1], 0, s[14:15]
	s_cmpk_eq_i32 s4, 0x800
	s_cbranch_scc0 .LBB0_1252
	s_mov_b64 s[4:5], 0

.LBB0_1259:
	s_or_b64 exec, exec, s[6:7]
	v_mov_b32_e32 v48, v56
	v_mov_b32_e32 v49, v52
	v_mul_f32_e32 v50, v76, v52
	v_fma_f32 v54, v4, v50, 0
	v_mov_b32_e32 v52, v57
	v_mul_f32_e32 v50, v77, v53
	v_pk_fma_f32 v[48:49], v[76:77], v[48:49], 0 op_sel_hi:[0,1,0]
	v_fmac_f32_e32 v54, v5, v50
	v_mul_f32_e32 v50, v74, v71
	v_pk_fma_f32 v[48:49], v[76:77], v[52:53], v[48:49] op_sel:[1,0,0]
	v_fmac_f32_e32 v54, v6, v50
	v_mul_f32_e32 v50, v75, v79
	v_pk_fma_f32 v[48:49], v[74:75], v[70:71], v[48:49] op_sel_hi:[0,1,1]
	v_fmac_f32_e32 v54, v7, v50
	v_mul_f32_e32 v50, v72, v81
	v_pk_fma_f32 v[48:49], v[74:75], v[78:79], v[48:49] op_sel:[1,0,0]
	v_fmac_f32_e32 v54, v0, v50
	v_mul_f32_e32 v50, v73, v83
	v_pk_fma_f32 v[48:49], v[72:73], v[80:81], v[48:49] op_sel_hi:[0,1,1]
	v_fmac_f32_e32 v54, v1, v50
	v_mul_f32_e32 v50, v68, v85
	v_pk_fma_f32 v[48:49], v[72:73], v[82:83], v[48:49] op_sel:[1,0,0]
	v_fmac_f32_e32 v54, v2, v50
	v_mul_f32_e32 v50, v69, v87
	v_pk_fma_f32 v[48:49], v[68:69], v[84:85], v[48:49] op_sel_hi:[0,1,1]
	v_fmac_f32_e32 v54, v3, v50
	v_pk_fma_f32 v[48:49], v[68:69], v[86:87], v[48:49] op_sel:[1,0,0]
	ds_bpermute_b32 v50, v144, v48
	ds_bpermute_b32 v52, v144, v54
	ds_bpermute_b32 v51, v144, v49
	v_cmp_eq_u32_e64 s[6:7], 0, v89
	s_waitcnt lgkmcnt(1)
	v_add_f32_e32 v52, v54, v52
	s_waitcnt lgkmcnt(0)
	v_pk_add_f32 v[48:49], v[48:49], v[50:51]
	ds_bpermute_b32 v50, v145, v48
	ds_bpermute_b32 v51, v145, v49
	ds_bpermute_b32 v53, v145, v52
	s_waitcnt lgkmcnt(1)
	v_pk_add_f32 v[48:49], v[48:49], v[50:51]
	s_waitcnt lgkmcnt(0)
	v_add_f32_e32 v52, v52, v53
	ds_bpermute_b32 v50, v146, v48
	ds_bpermute_b32 v51, v146, v49
	ds_bpermute_b32 v53, v146, v52
	s_and_saveexec_b64 s[38:39], s[6:7]
	s_cbranch_execz .LBB0_1262
	s_waitcnt lgkmcnt(1)
	v_pk_add_f32 v[48:49], v[48:49], v[50:51]
	s_cmp_lg_u32 s41, 0
	v_mul_f32_e32 v48, 0.25, v48
	v_mul_f32_e32 v49, 0.25, v49
	ds_write_b64 v147, v[48:49] offset:1344
	s_cbranch_scc1 .LBB0_1262
	s_lshl_b32 s43, s42, 3
	s_or_b32 s44, s43, s60
	s_ashr_i32 s45, s44, 31
	s_lshl_b64 s[44:45], s[44:45], 13
	s_add_u32 s44, s34, s44
	v_ashrrev_i32_e32 v99, 31, v98
	s_addc_u32 s45, s35, s45
	v_lshl_add_u64 v[48:49], v[98:99], 2, s[44:45]
	v_add_co_u32_e32 v48, vcc, 0xfb00000, v48
	s_waitcnt lgkmcnt(1)
	v_add_f32_e32 v50, v52, v53
	v_addc_co_u32_e32 v49, vcc, 0, v49, vcc
	global_store_dword v[48:49], v50, off

.LBB0_1269:
	s_or_b64 exec, exec, s[8:9]
	v_mov_b32_e32 v80, v88
	v_mov_b32_e32 v81, v84
	v_mul_f32_e32 v82, v128, v84
	v_fma_f32 v86, v4, v82, 0
	v_mov_b32_e32 v84, v89
	v_mul_f32_e32 v82, v129, v85
	v_pk_fma_f32 v[80:81], v[128:129], v[80:81], 0 op_sel_hi:[0,1,0]
	v_fmac_f32_e32 v86, v5, v82
	v_mul_f32_e32 v82, v126, v131
	v_pk_fma_f32 v[80:81], v[128:129], v[84:85], v[80:81] op_sel:[1,0,0]
	v_fmac_f32_e32 v86, v6, v82
	v_mul_f32_e32 v82, v127, v133
	v_pk_fma_f32 v[80:81], v[126:127], v[130:131], v[80:81] op_sel_hi:[0,1,1]
	v_fmac_f32_e32 v86, v7, v82
	v_mul_f32_e32 v82, v124, v135
	v_pk_fma_f32 v[80:81], v[126:127], v[132:133], v[80:81] op_sel:[1,0,0]
	v_fmac_f32_e32 v86, v0, v82
	v_mul_f32_e32 v82, v125, v137
	v_pk_fma_f32 v[80:81], v[124:125], v[134:135], v[80:81] op_sel_hi:[0,1,1]
	v_fmac_f32_e32 v86, v1, v82
	v_mul_f32_e32 v82, v122, v139
	v_pk_fma_f32 v[80:81], v[124:125], v[136:137], v[80:81] op_sel:[1,0,0]
	v_fmac_f32_e32 v86, v2, v82
	v_mul_f32_e32 v82, v123, v141
	v_pk_fma_f32 v[80:81], v[122:123], v[138:139], v[80:81] op_sel_hi:[0,1,1]
	v_fmac_f32_e32 v86, v3, v82
	v_pk_fma_f32 v[80:81], v[122:123], v[140:141], v[80:81] op_sel:[1,0,0]
	s_nop 1
	v_add_f32_dpp v84, v86, v86 quad_perm:[1,0,3,2] row_mask:0xf bank_mask:0xf
	v_add_f32_dpp v80, v80, v80 quad_perm:[1,0,3,2] row_mask:0xf bank_mask:0xf
	v_add_f32_dpp v81, v81, v81 quad_perm:[1,0,3,2] row_mask:0xf bank_mask:0xf
	v_add_f32_dpp v84, v84, v84 quad_perm:[2,3,0,1] row_mask:0xf bank_mask:0xf
	v_add_f32_dpp v80, v80, v80 quad_perm:[2,3,0,1] row_mask:0xf bank_mask:0xf
	v_add_f32_dpp v81, v81, v81 quad_perm:[2,3,0,1] row_mask:0xf bank_mask:0xf
	v_add_f32_dpp v84, v84, v84 row_half_mirror row_mask:0xf bank_mask:0xf
	v_add_f32_dpp v80, v80, v80 row_half_mirror row_mask:0xf bank_mask:0xf
	v_add_f32_dpp v81, v81, v81 row_half_mirror row_mask:0xf bank_mask:0xf
	s_and_saveexec_b64 s[8:9], s[6:7]
	s_cbranch_execz .LBB0_1271
	s_andn2_b64 vcc, exec, s[40:41]
	v_mul_f32_e32 v80, 0.25, v80
	v_mul_f32_e32 v81, 0.25, v81
	ds_write_b64 v94, v[80:81] offset:1344
	s_cbranch_vccz .LBB0_1292
